# GEMM K-loop restructured: 4 phases x 32 MFMA per two K-tiles (half the s_barriers), uniform vmcnt(8) waits, first-trip wait skip
# speedup vs baseline: 1.0353x; 1.0090x over previous
; #define PG8_STAGE(bufoff, gbase, voff) do { _Pragma("unroll") for (int _i = 0; _i < 2; ++_i) \
;     __builtin_amdgcn_global_load_lds((const unsigned*)((const char*)(gbase) + (voff)[_i]), (LAS unsigned*)(lds + (bufoff) + ldsw + _i * 8192), 16, 0, 0); } while (0)
; #define PG8_WAIT_V(n) asm volatile("s_waitcnt vmcnt(" #n ")" ::: "memory")
; #define PG8_BAR __builtin_amdgcn_s_barrier()
; template <class Epi>
; __device__ __forceinline__ void gemm_phase(LAS unsigned char* lds, const Gemm g, const StaticOrder& S, const Epi& E) {
;     ...
;   PG8_STAGE(PG8_SB(0, 0), cB, voffB); PG8_STAGE(PG8_SA(0, 0), cA, voffA); PG8_STAGE(PG8_SB(0, 1), cB + hstep, voffB); PG8_STAGE(PG8_SA(0, 1), cA + hstep, voffA);
;   if (wr == 1) PG8_BAR;
;   PG8_WAIT_V(4); PG8_BAR;
;   PG8_STAGE(PG8_SB(1, 0), cB + kstep, voffB); PG8_STAGE(PG8_SA(1, 0), cA + kstep, voffA); PG8_STAGE(PG8_SB(1, 1), cB + hstep + kstep, voffB);
;   PG8_WAIT_V(6); PG8_BAR;
;   for (;;) {
;     const bool has_next = S.next(ui + 1, nxt);
;     const char* nA = cA; const char* nB = cB;
;     if (has_next) { const char* qa = (const char*)g.A + (size_t)nxt.pm * tstep; const char* qb = (const char*)g.Bt + (size_t)nxt.pn * tstep; nA = nxt.swap ? qb : qa; nB = nxt.swap ? qa : qb; }
.LBB0_48:
	s_add_i32 m0, s15, 0x18000
	v_lshl_add_u64 v[0:1], v[0:1], 0, s[90:91]
	s_waitcnt vmcnt(2)
	s_barrier
	global_load_lds_dwordx4 v[0:1], off
	v_lshl_add_u64 v[0:1], v[2:3], 0, s[90:91]
	s_add_i32 m0, s15, 0x1a000
	s_add_i32 s29, s15, 0x8000
	global_load_lds_dwordx4 v[0:1], off
	v_lshl_add_u64 v[0:1], v[4:5], 0, s[90:91]
	s_mov_b32 m0, s29
	s_add_i32 s20, s15, 0xa000
	global_load_lds_dwordx4 v[0:1], off
	v_lshl_add_u64 v[0:1], v[6:7], 0, s[90:91]
	s_mov_b32 m0, s20
	v_bfe_u32 v19, v12, 4, 2
	global_load_lds_dwordx4 v[0:1], off
	s_add_i32 m0, s15, 0x1c000
	v_lshl_add_u64 v[0:1], v[8:9], 0, s[90:91]
	global_load_lds_dwordx4 v[0:1], off
	v_lshl_add_u64 v[0:1], v[10:11], 0, s[90:91]
	s_add_i32 m0, s15, 0x1e000
	v_and_b32_e32 v186, 15, v12
	global_load_lds_dwordx4 v[0:1], off
	v_lshlrev_b32_e32 v1, 4, v19
	v_lshlrev_b32_e32 v2, 2, v12
	s_and_b32 s11, s2, 3
	s_lshr_b32 s2, s1, 6
	v_lshl_or_b32 v1, v186, 6, v1
	s_lshl_b32 s1, s3, 13
	v_and_b32_e32 v2, 32, v2
	v_bitop3_b32 v3, v1, s1, v2 bitop3:0xde
	s_ashr_i32 s1, s0, 31
	s_lshl_b32 s28, s3, 6
	s_lshl_b32 s9, s11, 12
	s_add_i32 s21, s2, -2
	s_lshr_b32 s81, s92, 3
	s_lshl_b32 s12, s8, 3
	s_lshl_b64 s[4:5], s[0:1], 16
	s_add_u32 s3, s88, s4
	s_addc_u32 s10, s89, s5
	s_add_u32 s4, s3, 0x3f912100
	s_addc_u32 s5, s10, 0
	v_writelane_b32 v254, s4, 16
	v_bitop3_b32 v187, v1, s9, v2 bitop3:0xde
	v_lshlrev_b32_e32 v0, 3, v19
	v_writelane_b32 v254, s5, 17
	s_lshl_b32 s4, s0, 27
	s_and_b32 s4, s4, 0x8000000
	s_add_u32 s30, s88, 0x16852000
	s_addc_u32 s31, s89, 0
	s_add_u32 s4, s30, s4
	s_addc_u32 s5, s31, 0
	s_add_u32 s34, s88, 0xc300000
	v_writelane_b32 v254, s4, 23
	s_addc_u32 s35, s89, 0
	v_lshl_or_b32 v188, s11, 5, v0
	v_writelane_b32 v254, s5, 24
	s_add_u32 s4, s88, 0x16350000
	v_writelane_b32 v254, s4, 41
	s_addc_u32 s4, s89, 0
	v_writelane_b32 v254, s4, 14
	s_lshl_b32 s4, s0, 26
	s_and_b32 s6, s4, 0x4000000
	v_readlane_b32 s4, v254, 39
	v_readlane_b32 s5, v254, 40
	s_and_b64 s[4:5], s[4:5], exec
	s_cselect_b32 s4, 0x800, 0
	s_add_u32 s56, s88, s6
	s_addc_u32 s57, s89, 0
	s_add_u32 s4, s56, s4
	s_addc_u32 s5, s57, 0
	s_add_u32 s60, s4, 0x25852000
	s_addc_u32 s61, s5, 0
	s_lshl_b64 s[6:7], s[0:1], 25
	s_add_u32 s4, s88, s6
	s_addc_u32 s5, s89, s7
	s_add_u32 s4, s4, 0x35912000
	s_addc_u32 s5, s5, 0
	s_add_u32 s82, s3, 0x16300000
	s_addc_u32 s83, s10, 0
	s_add_u32 s68, s88, 0x1f852000
	s_addc_u32 s69, s89, 0
	v_writelane_b32 v254, s68, 30
	s_add_u32 s6, s34, s6
	s_addc_u32 s7, s35, s7
	v_writelane_b32 v254, s69, 31
	s_lshl_b64 s[0:1], s[0:1], 26
	v_readlane_b32 s68, v253, 0
	v_readlane_b32 s69, v253, 1
	s_add_u32 s0, s68, s0
	s_addc_u32 s1, s69, s1
	s_abs_i32 s3, s12
	v_cvt_f32_u32_e32 v4, s3
	v_writelane_b32 v254, s6, 18
	s_waitcnt vmcnt(0)
	v_readlane_b32 s70, v253, 2
	v_rcp_iflag_f32_e32 v1, v4
	v_writelane_b32 v254, s7, 19
	v_writelane_b32 v254, s0, 20
	s_mov_b32 s80, s12
	v_mul_f32_e32 v0, 0x4f7ffffe, v1
	v_cvt_u32_f32_e32 v0, v0
	v_writelane_b32 v254, s1, 21
	s_sub_i32 s0, 0, s3
	v_writelane_b32 v254, s11, 15
	v_readfirstlane_b32 s1, v0
	v_add_u32_e32 v0, v18, v16
	s_mul_i32 s0, s0, s1
	v_add_lshl_u32 v80, v0, v17, 1
	v_add_u32_e32 v0, v15, v13
	s_mul_hi_u32 s0, s1, s0
	v_lshl_add_u64 v[170:171], s[64:65], 0, v[80:81]
	v_add_lshl_u32 v80, v0, v14, 1
	s_mov_b32 s68, 0
	v_cmp_eq_u32_e64 s[6:7], 0, v19
	s_mov_b32 s93, s65
	s_bfe_i32 s69, s8, 0x1001c
	s_add_i32 s70, s1, s0
	v_lshl_add_u64 v[172:173], s[64:65], 0, v[80:81]
	v_add_u32_e32 v189, 0, v3
	v_readlane_b32 s71, v253, 3
	s_barrier
	s_branch .LBB0_51

; #define PG8_STAGE(bufoff, gbase, voff) do { _Pragma("unroll") for (int _i = 0; _i < 2; ++_i) \
;     __builtin_amdgcn_global_load_lds((const unsigned*)((const char*)(gbase) + (voff)[_i]), (LAS unsigned*)(lds + (bufoff) + ldsw + _i * 8192), 16, 0, 0); } while (0)
; #define PG8_LDA(dst, b, h) do { _Pragma("unroll") for (int m = 0; m < 4; ++m) _Pragma("unroll") for (int k = 0; k < 2; ++k) dst[m][k] = *(const LAS bf16x8*)(lds + PG8_SA(b, h) + aoff + m * 2048 + k * 1024); } while (0)
; #define PG8_LDB(dst, b, h) do { _Pragma("unroll") for (int n = 0; n < 2; ++n) _Pragma("unroll") for (int k = 0; k < 2; ++k) dst[n][k] = *(const LAS bf16x8*)(lds + PG8_SB(b, h) + boff + n * 2048 + k * 1024); } while (0)
; #define PG8_MMA(ai, bj, At, Bt) do { __builtin_amdgcn_s_setprio(1); _Pragma("unroll") for (int m = 0; m < 4; ++m) _Pragma("unroll") for (int n = 0; n < 2; ++n) _Pragma("unroll") for (int k = 0; k < 2; ++k) \
;     acc[ai][bj][m][n] = __builtin_amdgcn_mfma_f32_16x16x32_bf16(Bt[n][k], At[m][k], acc[ai][bj][m][n], 0, 0, 0); __builtin_amdgcn_s_setprio(0); } while (0)
; #define PG8_WAIT_L(n) asm volatile("s_waitcnt lgkmcnt(" #n ")" ::: "memory")
; #define PG8_BAR __builtin_amdgcn_s_barrier()
; #define PG8_SCHED __builtin_amdgcn_sched_barrier(0)
; template <class Epi>
; __device__ __forceinline__ void gemm_phase(LAS unsigned char* lds, const Gemm g, const StaticOrder& S, const Epi& E) {
;     ...
;       PG8_LDB(B0, 0, 0); PG8_SCHED; PG8_LDA(At, 0, 0); PG8_STAGE(PG8_SA(1, 1), a1 + hstep, voffA);
;       PG8_WAIT_L(8); PG8_BAR; PG8_WAIT_L(0); PG8_MMA(0, 0, At, B0); PG8_BAR; PG8_SCHED;
;       PG8_LDB(B1, 0, 1); PG8_STAGE(PG8_SB(0, 0), b2, voffB);
;       PG8_BAR; PG8_WAIT_L(0); PG8_MMA(0, 1, At, B1); PG8_BAR;
;       PG8_LDA(At, 0, 1); PG8_STAGE(PG8_SA(0, 0), a2, voffA);
;       PG8_BAR; PG8_WAIT_L(0); PG8_MMA(1, 0, At, B0); PG8_BAR; PG8_SCHED;
;       PG8_STAGE(PG8_SB(0, 1), b2 + hstep, voffB);
.LBB0_56:
	s_add_i32 s76, s10, 2
	s_add_u32 s12, s0, 0x80
	s_addc_u32 s11, s1, 0
	s_add_i32 s77, 0, 0x10000
	v_add_u32_e32 v80, s77, v187
	ds_read_b128 v[130:133], v80
	ds_read_b128 v[134:137], v80 offset:1024
	ds_read_b128 v[138:141], v80 offset:2048
	ds_read_b128 v[142:145], v80 offset:3072
	s_cmp_eq_u32 s21, s10
	s_cselect_b32 s10, s18, s12
	s_cselect_b32 s11, s19, s11
	s_cselect_b32 s13, s17, s75
	s_cselect_b32 s12, s16, s74
	v_lshl_add_u64 v[244:245], s[0:1], 0, v[172:173]
	s_add_i32 m0, s15, 0xc000
	ds_read_b128 v[146:149], v189
	ds_read_b128 v[150:153], v189 offset:1024
	ds_read_b128 v[154:157], v189 offset:2048
	ds_read_b128 v[158:161], v189 offset:3072
	ds_read_b128 v[174:177], v189 offset:4096
	ds_read_b128 v[178:181], v189 offset:5120
	ds_read_b128 v[182:185], v189 offset:6144
	ds_read_b128 v[190:193], v189 offset:7168
	global_load_lds_dwordx4 v[244:245], off
	v_lshl_add_u64 v[246:247], s[0:1], 0, v[170:171]
	s_add_i32 m0, s15, 0xe000
	ds_read_b128 v[194:197], v80 offset:16384
	ds_read_b128 v[198:201], v80 offset:17408
	ds_read_b128 v[202:205], v80 offset:18432
	ds_read_b128 v[206:209], v80 offset:19456
	global_load_lds_dwordx4 v[246:247], off
	s_cmp_lg_u32 s76, 2
	s_waitcnt lgkmcnt(0)
	s_cbranch_scc0 .Lkq1
	s_waitcnt vmcnt(8)
.Lkq1:
	s_barrier
	v_mfma_f32_16x16x32_bf16 v[126:129], v[130:133], v[146:149], v[126:129]
	v_mfma_f32_16x16x32_bf16 v[122:125], v[138:141], v[146:149], v[122:125]
	v_mfma_f32_16x16x32_bf16 v[118:121], v[130:133], v[154:157], v[118:121]
	v_mfma_f32_16x16x32_bf16 v[114:117], v[138:141], v[154:157], v[114:117]
	v_mfma_f32_16x16x32_bf16 v[110:113], v[130:133], v[174:177], v[110:113]
	v_mfma_f32_16x16x32_bf16 v[106:109], v[138:141], v[174:177], v[106:109]
	v_mfma_f32_16x16x32_bf16 v[102:105], v[130:133], v[182:185], v[102:105]
	v_mfma_f32_16x16x32_bf16 v[98:101], v[138:141], v[182:185], v[98:101]
	v_mfma_f32_16x16x32_bf16 v[126:129], v[134:137], v[150:153], v[126:129]
	v_mfma_f32_16x16x32_bf16 v[122:125], v[142:145], v[150:153], v[122:125]
	v_mfma_f32_16x16x32_bf16 v[118:121], v[134:137], v[158:161], v[118:121]
	v_mfma_f32_16x16x32_bf16 v[114:117], v[142:145], v[158:161], v[114:117]
	v_mfma_f32_16x16x32_bf16 v[110:113], v[134:137], v[178:181], v[110:113]
	v_mfma_f32_16x16x32_bf16 v[106:109], v[142:145], v[178:181], v[106:109]
	v_mfma_f32_16x16x32_bf16 v[102:105], v[134:137], v[190:193], v[102:105]
	v_mfma_f32_16x16x32_bf16 v[98:101], v[142:145], v[190:193], v[98:101]
	v_mfma_f32_16x16x32_bf16 v[60:63], v[194:197], v[146:149], v[60:63]
	v_mfma_f32_16x16x32_bf16 v[56:59], v[202:205], v[146:149], v[56:59]
	v_mfma_f32_16x16x32_bf16 v[52:55], v[194:197], v[154:157], v[52:55]
	v_mfma_f32_16x16x32_bf16 v[48:51], v[202:205], v[154:157], v[48:51]
	v_mfma_f32_16x16x32_bf16 v[44:47], v[194:197], v[174:177], v[44:47]
	v_mfma_f32_16x16x32_bf16 v[40:43], v[202:205], v[174:177], v[40:43]
	v_mfma_f32_16x16x32_bf16 v[36:39], v[194:197], v[182:185], v[36:39]
	v_mfma_f32_16x16x32_bf16 v[32:35], v[202:205], v[182:185], v[32:35]
	v_mfma_f32_16x16x32_bf16 v[60:63], v[198:201], v[150:153], v[60:63]
	v_mfma_f32_16x16x32_bf16 v[56:59], v[206:209], v[150:153], v[56:59]
	v_mfma_f32_16x16x32_bf16 v[52:55], v[198:201], v[158:161], v[52:55]
	v_mfma_f32_16x16x32_bf16 v[48:51], v[206:209], v[158:161], v[48:51]
	v_mfma_f32_16x16x32_bf16 v[44:47], v[198:201], v[178:181], v[44:47]
	v_mfma_f32_16x16x32_bf16 v[40:43], v[206:209], v[178:181], v[40:43]
	v_mfma_f32_16x16x32_bf16 v[36:39], v[198:201], v[190:193], v[36:39]
	v_mfma_f32_16x16x32_bf16 v[32:35], v[206:209], v[190:193], v[32:35]
	s_add_i32 s78, 0, 0x14000
	s_add_i32 s77, s77, s14
	s_barrier
	ds_read_b128 v[146:149], v189 offset:16384
	ds_read_b128 v[150:153], v189 offset:17408
	ds_read_b128 v[154:157], v189 offset:18432
	ds_read_b128 v[158:161], v189 offset:19456
	ds_read_b128 v[174:177], v189 offset:20480
	ds_read_b128 v[178:181], v189 offset:21504
	ds_read_b128 v[182:185], v189 offset:22528
	ds_read_b128 v[190:193], v189 offset:23552
	v_lshl_add_u64 v[210:211], s[12:13], 0, v[164:165]
	s_mov_b32 m0, s77
	v_lshl_add_u64 v[212:213], s[12:13], 0, v[168:169]
	global_load_lds_dwordx4 v[210:211], off
	s_add_i32 m0, s77, 0x2000
	v_lshl_add_u64 v[216:217], s[10:11], 0, v[162:163]
	global_load_lds_dwordx4 v[212:213], off
	s_mov_b32 m0, s15
	v_lshl_add_u64 v[232:233], s[10:11], 0, v[166:167]
	global_load_lds_dwordx4 v[216:217], off
	s_mov_b32 m0, s84
	s_add_u32 s12, s12, s64
	s_addc_u32 s13, s13, 0
	global_load_lds_dwordx4 v[232:233], off
	s_add_i32 s77, s78, s14
	v_lshl_add_u64 v[236:237], s[12:13], 0, v[164:165]
	s_mov_b32 m0, s77
	v_lshl_add_u64 v[242:243], s[12:13], 0, v[168:169]
	global_load_lds_dwordx4 v[236:237], off
	s_add_i32 m0, s77, 0x2000
	s_cmp_lg_u32 s76, 2
	global_load_lds_dwordx4 v[242:243], off
	s_waitcnt lgkmcnt(0)
	s_cbranch_scc0 .Lkq2
	s_waitcnt vmcnt(8)
; #define PG8_STAGE(bufoff, gbase, voff) do { _Pragma("unroll") for (int _i = 0; _i < 2; ++_i) \
;     __builtin_amdgcn_global_load_lds((const unsigned*)((const char*)(gbase) + (voff)[_i]), (LAS unsigned*)(lds + (bufoff) + ldsw + _i * 8192), 16, 0, 0); } while (0)
; #define PG8_LDA(dst, b, h) do { _Pragma("unroll") for (int m = 0; m < 4; ++m) _Pragma("unroll") for (int k = 0; k < 2; ++k) dst[m][k] = *(const LAS bf16x8*)(lds + PG8_SA(b, h) + aoff + m * 2048 + k * 1024); } while (0)
; #define PG8_LDB(dst, b, h) do { _Pragma("unroll") for (int n = 0; n < 2; ++n) _Pragma("unroll") for (int k = 0; k < 2; ++k) dst[n][k] = *(const LAS bf16x8*)(lds + PG8_SB(b, h) + boff + n * 2048 + k * 1024); } while (0)
; #define PG8_MMA(ai, bj, At, Bt) do { __builtin_amdgcn_s_setprio(1); _Pragma("unroll") for (int m = 0; m < 4; ++m) _Pragma("unroll") for (int n = 0; n < 2; ++n) _Pragma("unroll") for (int k = 0; k < 2; ++k) \
;     acc[ai][bj][m][n] = __builtin_amdgcn_mfma_f32_16x16x32_bf16(Bt[n][k], At[m][k], acc[ai][bj][m][n], 0, 0, 0); __builtin_amdgcn_s_setprio(0); } while (0)
; #define PG8_WAIT_V(n) asm volatile("s_waitcnt vmcnt(" #n ")" ::: "memory")
; #define PG8_WAIT_L(n) asm volatile("s_waitcnt lgkmcnt(" #n ")" ::: "memory")
; #define PG8_BAR __builtin_amdgcn_s_barrier()
; #define PG8_SCHED __builtin_amdgcn_sched_barrier(0)
; template <class Epi>
; __device__ __forceinline__ void gemm_phase(LAS unsigned char* lds, const Gemm g, const StaticOrder& S, const Epi& E) {
;     ...
;       PG8_BAR; PG8_WAIT_L(0); PG8_MMA(1, 0, At, B0); PG8_BAR; PG8_SCHED;
;       PG8_STAGE(PG8_SB(0, 1), b2 + hstep, voffB);
;       PG8_WAIT_V(6); PG8_BAR; PG8_MMA(1, 1, At, B1); PG8_BAR;
;       PG8_LDB(B0, 1, 0); PG8_SCHED; PG8_LDA(At, 1, 0); PG8_STAGE(PG8_SA(0, 1), a2 + hstep, voffA);
;       PG8_WAIT_L(8); PG8_BAR; PG8_WAIT_L(0); PG8_MMA(0, 0, At, B0); PG8_BAR; PG8_SCHED;
;       PG8_LDB(B1, 1, 1); PG8_STAGE(PG8_SB(1, 0), b3, voffB);
;       PG8_BAR; PG8_WAIT_L(0); PG8_MMA(0, 1, At, B1); PG8_BAR;
;       PG8_LDA(At, 1, 1); PG8_STAGE(PG8_SA(1, 0), a3, voffA);
;       PG8_BAR; PG8_WAIT_L(0); PG8_MMA(1, 0, At, B0); PG8_BAR; PG8_SCHED;
.Lkq2:
	s_barrier
	v_mfma_f32_16x16x32_bf16 v[94:97], v[130:133], v[146:149], v[94:97]
	v_mfma_f32_16x16x32_bf16 v[90:93], v[138:141], v[146:149], v[90:93]
	v_mfma_f32_16x16x32_bf16 v[86:89], v[130:133], v[154:157], v[86:89]
	v_mfma_f32_16x16x32_bf16 v[82:85], v[138:141], v[154:157], v[82:85]
	v_mfma_f32_16x16x32_bf16 v[76:79], v[130:133], v[174:177], v[76:79]
	v_mfma_f32_16x16x32_bf16 v[72:75], v[138:141], v[174:177], v[72:75]
	v_mfma_f32_16x16x32_bf16 v[68:71], v[130:133], v[182:185], v[68:71]
	v_mfma_f32_16x16x32_bf16 v[64:67], v[138:141], v[182:185], v[64:67]
	v_mfma_f32_16x16x32_bf16 v[94:97], v[134:137], v[150:153], v[94:97]
	v_mfma_f32_16x16x32_bf16 v[90:93], v[142:145], v[150:153], v[90:93]
	v_mfma_f32_16x16x32_bf16 v[86:89], v[134:137], v[158:161], v[86:89]
	v_mfma_f32_16x16x32_bf16 v[82:85], v[142:145], v[158:161], v[82:85]
	v_mfma_f32_16x16x32_bf16 v[76:79], v[134:137], v[178:181], v[76:79]
	v_mfma_f32_16x16x32_bf16 v[72:75], v[142:145], v[178:181], v[72:75]
	v_mfma_f32_16x16x32_bf16 v[68:71], v[134:137], v[190:193], v[68:71]
	v_mfma_f32_16x16x32_bf16 v[64:67], v[142:145], v[190:193], v[64:67]
	v_mfma_f32_16x16x32_bf16 v[28:31], v[194:197], v[146:149], v[28:31]
	v_mfma_f32_16x16x32_bf16 v[24:27], v[202:205], v[146:149], v[24:27]
	v_mfma_f32_16x16x32_bf16 v[20:23], v[194:197], v[154:157], v[20:23]
	v_mfma_f32_16x16x32_bf16 v[16:19], v[202:205], v[154:157], v[16:19]
	v_mfma_f32_16x16x32_bf16 v[12:15], v[194:197], v[174:177], v[12:15]
	v_mfma_f32_16x16x32_bf16 v[8:11], v[202:205], v[174:177], v[8:11]
	v_mfma_f32_16x16x32_bf16 v[4:7], v[194:197], v[182:185], v[4:7]
	v_mfma_f32_16x16x32_bf16 v[0:3], v[202:205], v[182:185], v[0:3]
	v_mfma_f32_16x16x32_bf16 v[28:31], v[198:201], v[150:153], v[28:31]
	v_mfma_f32_16x16x32_bf16 v[24:27], v[206:209], v[150:153], v[24:27]
	v_mfma_f32_16x16x32_bf16 v[20:23], v[198:201], v[158:161], v[20:23]
	v_mfma_f32_16x16x32_bf16 v[16:19], v[206:209], v[158:161], v[16:19]
	v_mfma_f32_16x16x32_bf16 v[12:15], v[198:201], v[178:181], v[12:15]
	v_mfma_f32_16x16x32_bf16 v[8:11], v[206:209], v[178:181], v[8:11]
	v_mfma_f32_16x16x32_bf16 v[4:7], v[198:201], v[190:193], v[4:7]
	v_mfma_f32_16x16x32_bf16 v[0:3], v[206:209], v[190:193], v[0:3]
	s_add_i32 s12, 0, 0x18000
	v_add_u32_e32 v80, s12, v187
	s_barrier
	ds_read_b128 v[130:133], v80
	ds_read_b128 v[134:137], v80 offset:1024
	ds_read_b128 v[138:141], v80 offset:2048
	ds_read_b128 v[142:145], v80 offset:3072
	s_add_u32 s10, s10, s64
	s_addc_u32 s11, s11, 0
	s_mov_b32 m0, s99
	v_lshl_add_u64 v[244:245], s[10:11], 0, v[162:163]
	ds_read_b128 v[146:149], v189 offset:32768
	ds_read_b128 v[150:153], v189 offset:33792
	ds_read_b128 v[154:157], v189 offset:34816
	ds_read_b128 v[158:161], v189 offset:35840
	ds_read_b128 v[174:177], v189 offset:36864
	ds_read_b128 v[178:181], v189 offset:37888
	ds_read_b128 v[182:185], v189 offset:38912
	ds_read_b128 v[190:193], v189 offset:39936
	global_load_lds_dwordx4 v[244:245], off
	v_lshl_add_u64 v[246:247], s[10:11], 0, v[166:167]
	s_mov_b32 m0, s33
	ds_read_b128 v[194:197], v80 offset:16384
	ds_read_b128 v[198:201], v80 offset:17408
	ds_read_b128 v[202:205], v80 offset:18432
	ds_read_b128 v[206:209], v80 offset:19456
	global_load_lds_dwordx4 v[246:247], off
	s_waitcnt lgkmcnt(0)
	s_waitcnt vmcnt(8)
	s_barrier
	v_mfma_f32_16x16x32_bf16 v[126:129], v[130:133], v[146:149], v[126:129]
	v_mfma_f32_16x16x32_bf16 v[122:125], v[138:141], v[146:149], v[122:125]
	v_mfma_f32_16x16x32_bf16 v[118:121], v[130:133], v[154:157], v[118:121]
	v_mfma_f32_16x16x32_bf16 v[114:117], v[138:141], v[154:157], v[114:117]
	v_mfma_f32_16x16x32_bf16 v[110:113], v[130:133], v[174:177], v[110:113]
	v_mfma_f32_16x16x32_bf16 v[106:109], v[138:141], v[174:177], v[106:109]
	v_mfma_f32_16x16x32_bf16 v[102:105], v[130:133], v[182:185], v[102:105]
	v_mfma_f32_16x16x32_bf16 v[98:101], v[138:141], v[182:185], v[98:101]
	v_mfma_f32_16x16x32_bf16 v[126:129], v[134:137], v[150:153], v[126:129]
	v_mfma_f32_16x16x32_bf16 v[122:125], v[142:145], v[150:153], v[122:125]
	v_mfma_f32_16x16x32_bf16 v[118:121], v[134:137], v[158:161], v[118:121]
	v_mfma_f32_16x16x32_bf16 v[114:117], v[142:145], v[158:161], v[114:117]
	v_mfma_f32_16x16x32_bf16 v[110:113], v[134:137], v[178:181], v[110:113]
	v_mfma_f32_16x16x32_bf16 v[106:109], v[142:145], v[178:181], v[106:109]
	v_mfma_f32_16x16x32_bf16 v[102:105], v[134:137], v[190:193], v[102:105]
	v_mfma_f32_16x16x32_bf16 v[98:101], v[142:145], v[190:193], v[98:101]
	v_mfma_f32_16x16x32_bf16 v[60:63], v[194:197], v[146:149], v[60:63]
	v_mfma_f32_16x16x32_bf16 v[56:59], v[202:205], v[146:149], v[56:59]
	v_mfma_f32_16x16x32_bf16 v[52:55], v[194:197], v[154:157], v[52:55]
	v_mfma_f32_16x16x32_bf16 v[48:51], v[202:205], v[154:157], v[48:51]
	v_mfma_f32_16x16x32_bf16 v[44:47], v[194:197], v[174:177], v[44:47]
	v_mfma_f32_16x16x32_bf16 v[40:43], v[202:205], v[174:177], v[40:43]
	v_mfma_f32_16x16x32_bf16 v[36:39], v[194:197], v[182:185], v[36:39]
	v_mfma_f32_16x16x32_bf16 v[32:35], v[202:205], v[182:185], v[32:35]
	v_mfma_f32_16x16x32_bf16 v[60:63], v[198:201], v[150:153], v[60:63]
	v_mfma_f32_16x16x32_bf16 v[56:59], v[206:209], v[150:153], v[56:59]
	v_mfma_f32_16x16x32_bf16 v[52:55], v[198:201], v[158:161], v[52:55]
	v_mfma_f32_16x16x32_bf16 v[48:51], v[206:209], v[158:161], v[48:51]
	v_mfma_f32_16x16x32_bf16 v[44:47], v[198:201], v[178:181], v[44:47]
	v_mfma_f32_16x16x32_bf16 v[40:43], v[206:209], v[178:181], v[40:43]
	v_mfma_f32_16x16x32_bf16 v[36:39], v[198:201], v[190:193], v[36:39]
	v_mfma_f32_16x16x32_bf16 v[32:35], v[206:209], v[190:193], v[32:35]
	s_add_i32 s10, 0, 0x1c000
	s_add_i32 s11, s12, s14
	s_barrier
; #define PG8_STAGE(bufoff, gbase, voff) do { _Pragma("unroll") for (int _i = 0; _i < 2; ++_i) \
;     __builtin_amdgcn_global_load_lds((const unsigned*)((const char*)(gbase) + (voff)[_i]), (LAS unsigned*)(lds + (bufoff) + ldsw + _i * 8192), 16, 0, 0); } while (0)
; #define PG8_LDA(dst, b, h) do { _Pragma("unroll") for (int m = 0; m < 4; ++m) _Pragma("unroll") for (int k = 0; k < 2; ++k) dst[m][k] = *(const LAS bf16x8*)(lds + PG8_SA(b, h) + aoff + m * 2048 + k * 1024); } while (0)
; #define PG8_LDB(dst, b, h) do { _Pragma("unroll") for (int n = 0; n < 2; ++n) _Pragma("unroll") for (int k = 0; k < 2; ++k) dst[n][k] = *(const LAS bf16x8*)(lds + PG8_SB(b, h) + boff + n * 2048 + k * 1024); } while (0)
; #define PG8_MMA(ai, bj, At, Bt) do { __builtin_amdgcn_s_setprio(1); _Pragma("unroll") for (int m = 0; m < 4; ++m) _Pragma("unroll") for (int n = 0; n < 2; ++n) _Pragma("unroll") for (int k = 0; k < 2; ++k) \
;     acc[ai][bj][m][n] = __builtin_amdgcn_mfma_f32_16x16x32_bf16(Bt[n][k], At[m][k], acc[ai][bj][m][n], 0, 0, 0); __builtin_amdgcn_s_setprio(0); } while (0)
; #define PG8_BAR __builtin_amdgcn_s_barrier()
; template <class Epi>
; __device__ __forceinline__ void gemm_phase(LAS unsigned char* lds, const Gemm g, const StaticOrder& S, const Epi& E) {
;     ...
;       PG8_LDB(B0, 1, 0); PG8_SCHED; PG8_LDA(At, 1, 0); PG8_STAGE(PG8_SA(0, 1), a2 + hstep, voffA);
;       PG8_WAIT_L(8); PG8_BAR; PG8_WAIT_L(0); PG8_MMA(0, 0, At, B0); PG8_BAR; PG8_SCHED;
;       PG8_LDB(B1, 1, 1); PG8_STAGE(PG8_SB(1, 0), b3, voffB);
;       PG8_BAR; PG8_WAIT_L(0); PG8_MMA(0, 1, At, B1); PG8_BAR;
;       PG8_LDA(At, 1, 1); PG8_STAGE(PG8_SA(1, 0), a3, voffA);
;       PG8_BAR; PG8_WAIT_L(0); PG8_MMA(1, 0, At, B0); PG8_BAR; PG8_SCHED;
;       PG8_STAGE(PG8_SB(1, 1), b3 + hstep, voffB);
;       PG8_WAIT_V(6); PG8_BAR; PG8_MMA(1, 1, At, B1); PG8_BAR;
;   __device__ __forceinline__ void operator()(const f32x4 (&acc)[2][2][4][2], const pg8::Unit& u, int wr, int wc, int fr, int fq) const {
;     ...
;       float* xo = P->out + (size_t)slice * TS * DM; const u16* x2b = (const u16*)(ws + O_X2B) + (size_t)slice * TS * DM;
; #pragma unroll
;       for (int ai = 0; ai < 2; ++ai) {
;         u32x4 xv[4][2];
; #pragma unroll
;         for (int m = 0; m < 4; ++m)
; #pragma unroll
;           for (int bj = 0; bj < 2; ++bj) xv[m][bj] = *(const u32x4*)(x2b + (size_t)(row0 + ai * 128 + m * 16) * DM + col0 + bj * 128);
	ds_read_b128 v[146:149], v189 offset:49152
	ds_read_b128 v[150:153], v189 offset:50176
	ds_read_b128 v[154:157], v189 offset:51200
	ds_read_b128 v[158:161], v189 offset:52224
	ds_read_b128 v[174:177], v189 offset:53248
	ds_read_b128 v[178:181], v189 offset:54272
	ds_read_b128 v[182:185], v189 offset:55296
	ds_read_b128 v[190:193], v189 offset:56320
	v_lshl_add_u64 v[210:211], v[210:211], 0, s[90:91]
	s_mov_b32 m0, s11
	v_lshl_add_u64 v[212:213], v[212:213], 0, s[90:91]
	global_load_lds_dwordx4 v[210:211], off
	s_add_i32 m0, s11, 0x2000
	v_lshl_add_u64 v[216:217], v[216:217], 0, s[90:91]
	global_load_lds_dwordx4 v[212:213], off
	s_mov_b32 m0, s29
	v_lshl_add_u64 v[232:233], v[232:233], 0, s[90:91]
	global_load_lds_dwordx4 v[216:217], off
	s_mov_b32 m0, s20
	s_add_i32 s10, s10, s14
	global_load_lds_dwordx4 v[232:233], off
	v_lshl_add_u64 v[244:245], v[236:237], 0, s[90:91]
	s_mov_b32 m0, s10
	v_lshl_add_u64 v[246:247], v[242:243], 0, s[90:91]
	global_load_lds_dwordx4 v[244:245], off
	s_add_i32 m0, s10, 0x2000
	s_nop 0
	global_load_lds_dwordx4 v[246:247], off
	s_waitcnt lgkmcnt(0)
	s_waitcnt vmcnt(8)
	s_barrier
	v_mfma_f32_16x16x32_bf16 v[94:97], v[130:133], v[146:149], v[94:97]
	v_mfma_f32_16x16x32_bf16 v[90:93], v[138:141], v[146:149], v[90:93]
	v_mfma_f32_16x16x32_bf16 v[86:89], v[130:133], v[154:157], v[86:89]
	v_mfma_f32_16x16x32_bf16 v[82:85], v[138:141], v[154:157], v[82:85]
	v_mfma_f32_16x16x32_bf16 v[76:79], v[130:133], v[174:177], v[76:79]
	v_mfma_f32_16x16x32_bf16 v[72:75], v[138:141], v[174:177], v[72:75]
	v_mfma_f32_16x16x32_bf16 v[68:71], v[130:133], v[182:185], v[68:71]
	v_mfma_f32_16x16x32_bf16 v[64:67], v[138:141], v[182:185], v[64:67]
	v_mfma_f32_16x16x32_bf16 v[94:97], v[134:137], v[150:153], v[94:97]
	v_mfma_f32_16x16x32_bf16 v[90:93], v[142:145], v[150:153], v[90:93]
	v_mfma_f32_16x16x32_bf16 v[86:89], v[134:137], v[158:161], v[86:89]
	v_mfma_f32_16x16x32_bf16 v[82:85], v[142:145], v[158:161], v[82:85]
	v_mfma_f32_16x16x32_bf16 v[76:79], v[134:137], v[178:181], v[76:79]
	v_mfma_f32_16x16x32_bf16 v[72:75], v[142:145], v[178:181], v[72:75]
	v_mfma_f32_16x16x32_bf16 v[68:71], v[134:137], v[190:193], v[68:71]
	v_mfma_f32_16x16x32_bf16 v[64:67], v[142:145], v[190:193], v[64:67]
	v_mfma_f32_16x16x32_bf16 v[28:31], v[194:197], v[146:149], v[28:31]
	v_mfma_f32_16x16x32_bf16 v[24:27], v[202:205], v[146:149], v[24:27]
	v_mfma_f32_16x16x32_bf16 v[20:23], v[194:197], v[154:157], v[20:23]
	v_mfma_f32_16x16x32_bf16 v[16:19], v[202:205], v[154:157], v[16:19]
	v_mfma_f32_16x16x32_bf16 v[12:15], v[194:197], v[174:177], v[12:15]
	v_mfma_f32_16x16x32_bf16 v[8:11], v[202:205], v[174:177], v[8:11]
	v_mfma_f32_16x16x32_bf16 v[4:7], v[194:197], v[182:185], v[4:7]
	v_mfma_f32_16x16x32_bf16 v[0:3], v[202:205], v[182:185], v[0:3]
	v_mfma_f32_16x16x32_bf16 v[28:31], v[198:201], v[150:153], v[28:31]
	v_mfma_f32_16x16x32_bf16 v[24:27], v[206:209], v[150:153], v[24:27]
	v_mfma_f32_16x16x32_bf16 v[20:23], v[198:201], v[158:161], v[20:23]
	v_mfma_f32_16x16x32_bf16 v[16:19], v[206:209], v[158:161], v[16:19]
	v_mfma_f32_16x16x32_bf16 v[12:15], v[198:201], v[178:181], v[12:15]
	v_mfma_f32_16x16x32_bf16 v[8:11], v[206:209], v[178:181], v[8:11]
	v_mfma_f32_16x16x32_bf16 v[4:7], v[198:201], v[190:193], v[4:7]
	v_mfma_f32_16x16x32_bf16 v[0:3], v[206:209], v[190:193], v[0:3]
	s_add_u32 s74, s74, 0x100
	s_addc_u32 s75, s75, 0
	s_add_u32 s0, s0, 0x100
	s_addc_u32 s1, s1, 0
	s_cmp_ge_u32 s76, s2
	s_mov_b32 s10, s76
	s_barrier
	s_cbranch_scc0 .LBB0_56
	s_cmp_lg_u32 s71, 0
	s_cselect_b64 s[0:1], -1, 0
	s_cmp_eq_u32 s71, 0
	s_cselect_b32 s10, s73, s72
	s_cselect_b32 s11, s72, s73
	s_lshl_b32 s71, s10, 8
	s_add_i32 s71, s71, s28
	v_or_b32_e32 v176, s71, v186
	v_lshl_or_b32 v174, s11, 8, v188
	s_cmp_lt_i32 s98, 2
	s_mov_b64 s[10:11], -1
	s_cbranch_scc1 .LBB0_151
	s_cmp_lt_i32 s98, 4
	s_cbranch_scc1 .LBB0_84
	s_cmp_lt_i32 s98, 5
	s_cbranch_scc1 .LBB0_65
	s_cmp_lg_u32 s98, 5
	s_cbranch_scc0 .LBB0_62
	v_readlane_b32 s10, v254, 18
	v_ashrrev_i32_e32 v175, 31, v174
	v_readlane_b32 s11, v254, 19
	v_ashrrev_i32_e32 v177, 31, v176
	v_lshlrev_b64 v[130:131], 11, v[176:177]
	v_lshl_add_u64 v[136:137], v[174:175], 1, s[10:11]
	v_or_b32_e32 v190, 16, v176
	v_lshl_add_u64 v[130:131], v[136:137], 0, v[130:131]
	v_ashrrev_i32_e32 v191, 31, v190
	flat_load_dwordx4 v[138:141], v[130:131]
	flat_load_dwordx4 v[142:145], v[130:131] offset:256
	v_lshlrev_b64 v[130:131], 11, v[190:191]
	v_or_b32_e32 v192, 32, v176
	v_lshl_add_u64 v[130:131], v[136:137], 0, v[130:131]
	v_ashrrev_i32_e32 v193, 31, v192
	flat_load_dwordx4 v[146:149], v[130:131]
	flat_load_dwordx4 v[150:153], v[130:131] offset:256
	v_lshlrev_b64 v[130:131], 11, v[192:193]
	v_or_b32_e32 v194, 48, v176
	v_lshl_add_u64 v[130:131], v[136:137], 0, v[130:131]
	v_ashrrev_i32_e32 v195, 31, v194
	flat_load_dwordx4 v[154:157], v[130:131]
	flat_load_dwordx4 v[158:161], v[130:131] offset:256
	v_lshlrev_b64 v[130:131], 11, v[194:195]
	v_lshl_add_u64 v[130:131], v[136:137], 0, v[130:131]
	flat_load_dwordx4 v[178:181], v[130:131]
	s_nop 0
	flat_load_dwordx4 v[130:133], v[130:131] offset:256
	v_readlane_b32 s10, v254, 20
	v_readlane_b32 s11, v254, 21
	s_nop 1
	v_lshl_add_u64 v[134:135], v[174:175], 2, s[10:11]
	v_lshlrev_b64 v[182:183], 12, v[176:177]
	v_lshl_add_u64 v[196:197], v[134:135], 0, v[182:183]
	s_waitcnt vmcnt(0) lgkmcnt(0)
; __device__ __forceinline__ float lo16(unsigned v) { return __uint_as_float(v << 16); }
; __device__ __forceinline__ float hi16(unsigned v) { return __uint_as_float(v & 0xffff0000u); }
;   __device__ __forceinline__ void operator()(const f32x4 (&acc)[2][2][4][2], const pg8::Unit& u, int wr, int wc, int fr, int fq) const {
;     ...
;       float* xo = P->out + (size_t)slice * TS * DM; const u16* x2b = (const u16*)(ws + O_X2B) + (size_t)slice * TS * DM;
; #pragma unroll
;       for (int ai = 0; ai < 2; ++ai) {
;         u32x4 xv[4][2];
; #pragma unroll
;         for (int m = 0; m < 4; ++m)
; #pragma unroll
;           for (int bj = 0; bj < 2; ++bj) xv[m][bj] = *(const u32x4*)(x2b + (size_t)(row0 + ai * 128 + m * 16) * DM + col0 + bj * 128);
;         __builtin_amdgcn_sched_barrier(0);
; #pragma unroll
;         for (int m = 0; m < 4; ++m) {
;           const int row = row0 + ai * 128 + m * 16;
; #pragma unroll
;           for (int bj = 0; bj < 2; ++bj) {
;             float* d = xo + (size_t)row * DM + col0 + bj * 128;
;             const u32x4 x4 = xv[m][bj];
;             f32x4 o0 = acc[ai][bj][m][0], o1 = acc[ai][bj][m][1];
;             o0[0] += lo16(x4.x); o0[1] += hi16(x4.x); o0[2] += lo16(x4.y); o0[3] += hi16(x4.y); o1[0] += lo16(x4.z); o1[1] += hi16(x4.z); o1[2] += lo16(x4.w); o1[3] += hi16(x4.w);
;             *(f32x4*)d = o0; *(f32x4*)(d + 4) = o1;
;           }
;         }
	v_lshlrev_b32_e32 v182, 16, v138
	v_and_b32_e32 v183, 0xffff0000, v138
	v_lshlrev_b32_e32 v138, 16, v139
	v_and_b32_e32 v139, 0xffff0000, v139
	v_pk_add_f32 v[184:185], v[128:129], v[138:139]
	v_lshlrev_b32_e32 v138, 16, v140
	v_and_b32_e32 v139, 0xffff0000, v140
	v_lshlrev_b32_e32 v140, 16, v141
	v_and_b32_e32 v141, 0xffff0000, v141
	v_pk_add_f32 v[182:183], v[126:127], v[182:183]
	v_pk_add_f32 v[138:139], v[122:123], v[138:139]
	v_pk_add_f32 v[140:141], v[124:125], v[140:141]
	global_store_dwordx4 v[196:197], v[182:185], off
	global_store_dwordx4 v[196:197], v[138:141], off offset:16
	s_nop 1
	v_lshlrev_b32_e32 v138, 16, v142
	v_and_b32_e32 v139, 0xffff0000, v142
	v_lshlrev_b32_e32 v140, 16, v143
	v_and_b32_e32 v141, 0xffff0000, v143
	v_pk_add_f32 v[138:139], v[60:61], v[138:139]
	v_pk_add_f32 v[140:141], v[62:63], v[140:141]
	v_lshlrev_b32_e32 v142, 16, v144
	v_and_b32_e32 v143, 0xffff0000, v144
	v_lshlrev_b32_e32 v144, 16, v145
	v_and_b32_e32 v145, 0xffff0000, v145
	v_pk_add_f32 v[142:143], v[56:57], v[142:143]
	v_pk_add_f32 v[144:145], v[58:59], v[144:145]
	global_store_dwordx4 v[196:197], v[138:141], off offset:512
	global_store_dwordx4 v[196:197], v[142:145], off offset:528
	s_nop 0
	v_lshlrev_b64 v[138:139], 12, v[190:191]
	v_lshl_add_u64 v[182:183], v[134:135], 0, v[138:139]
	v_lshlrev_b32_e32 v138, 16, v146
	v_and_b32_e32 v139, 0xffff0000, v146
	v_lshlrev_b32_e32 v140, 16, v147
	v_and_b32_e32 v141, 0xffff0000, v147
	v_pk_add_f32 v[138:139], v[118:119], v[138:139]
	v_pk_add_f32 v[140:141], v[120:121], v[140:141]
	v_lshlrev_b32_e32 v142, 16, v148
	v_and_b32_e32 v143, 0xffff0000, v148
	v_lshlrev_b32_e32 v144, 16, v149
	v_and_b32_e32 v145, 0xffff0000, v149
	v_pk_add_f32 v[142:143], v[114:115], v[142:143]
	v_pk_add_f32 v[144:145], v[116:117], v[144:145]
	global_store_dwordx4 v[182:183], v[138:141], off
	global_store_dwordx4 v[182:183], v[142:145], off offset:16
	s_nop 0
	v_lshlrev_b32_e32 v138, 16, v150
	v_and_b32_e32 v139, 0xffff0000, v150
	v_lshlrev_b32_e32 v140, 16, v151
	v_and_b32_e32 v141, 0xffff0000, v151
	v_pk_add_f32 v[138:139], v[52:53], v[138:139]
	v_pk_add_f32 v[140:141], v[54:55], v[140:141]
	v_lshlrev_b32_e32 v142, 16, v152
	v_and_b32_e32 v143, 0xffff0000, v152
	v_lshlrev_b32_e32 v144, 16, v153
	v_and_b32_e32 v145, 0xffff0000, v153
	v_pk_add_f32 v[142:143], v[48:49], v[142:143]
	v_pk_add_f32 v[144:145], v[50:51], v[144:145]
	global_store_dwordx4 v[182:183], v[138:141], off offset:512
	global_store_dwordx4 v[182:183], v[142:145], off offset:528
	s_nop 0
	v_lshlrev_b64 v[138:139], 12, v[192:193]
	v_lshl_add_u64 v[146:147], v[134:135], 0, v[138:139]
	v_lshlrev_b32_e32 v138, 16, v154
	v_and_b32_e32 v139, 0xffff0000, v154
	v_lshlrev_b32_e32 v140, 16, v155
	v_and_b32_e32 v141, 0xffff0000, v155
	v_pk_add_f32 v[138:139], v[110:111], v[138:139]
	v_pk_add_f32 v[140:141], v[112:113], v[140:141]
	v_lshlrev_b32_e32 v142, 16, v156
	v_and_b32_e32 v143, 0xffff0000, v156
	v_lshlrev_b32_e32 v144, 16, v157
	v_and_b32_e32 v145, 0xffff0000, v157
	v_pk_add_f32 v[142:143], v[106:107], v[142:143]
	v_pk_add_f32 v[144:145], v[108:109], v[144:145]
	global_store_dwordx4 v[146:147], v[138:141], off
	global_store_dwordx4 v[146:147], v[142:145], off offset:16
	s_nop 0
	v_lshlrev_b32_e32 v138, 16, v158
	v_and_b32_e32 v139, 0xffff0000, v158
	v_lshlrev_b32_e32 v140, 16, v159
	v_and_b32_e32 v141, 0xffff0000, v159
	v_pk_add_f32 v[138:139], v[44:45], v[138:139]
	v_pk_add_f32 v[140:141], v[46:47], v[140:141]
	v_lshlrev_b32_e32 v142, 16, v160
	v_and_b32_e32 v143, 0xffff0000, v160
	v_lshlrev_b32_e32 v144, 16, v161
	v_and_b32_e32 v145, 0xffff0000, v161
	v_pk_add_f32 v[142:143], v[40:41], v[142:143]
	v_pk_add_f32 v[144:145], v[42:43], v[144:145]
	global_store_dwordx4 v[146:147], v[138:141], off offset:512
	global_store_dwordx4 v[146:147], v[142:145], off offset:528
	s_nop 0
	v_lshlrev_b64 v[138:139], 12, v[194:195]
	v_lshl_add_u64 v[146:147], v[134:135], 0, v[138:139]
	v_lshlrev_b32_e32 v138, 16, v178
	v_and_b32_e32 v139, 0xffff0000, v178
	v_lshlrev_b32_e32 v140, 16, v179
	v_and_b32_e32 v141, 0xffff0000, v179
	v_pk_add_f32 v[138:139], v[102:103], v[138:139]
	v_pk_add_f32 v[140:141], v[104:105], v[140:141]
	v_lshlrev_b32_e32 v142, 16, v180
	v_and_b32_e32 v143, 0xffff0000, v180
	v_lshlrev_b32_e32 v144, 16, v181
	v_and_b32_e32 v145, 0xffff0000, v181
	v_pk_add_f32 v[142:143], v[98:99], v[142:143]
	v_pk_add_f32 v[144:145], v[100:101], v[144:145]
	global_store_dwordx4 v[146:147], v[138:141], off
	global_store_dwordx4 v[146:147], v[142:145], off offset:16
	s_nop 0
	v_lshlrev_b32_e32 v138, 16, v130
	v_and_b32_e32 v139, 0xffff0000, v130
	v_lshlrev_b32_e32 v130, 16, v131
	v_and_b32_e32 v131, 0xffff0000, v131
	v_pk_add_f32 v[138:139], v[36:37], v[138:139]
	v_pk_add_f32 v[140:141], v[38:39], v[130:131]
	v_lshlrev_b32_e32 v130, 16, v132
	v_and_b32_e32 v131, 0xffff0000, v132
	v_lshlrev_b32_e32 v132, 16, v133
	v_and_b32_e32 v133, 0xffff0000, v133
	v_pk_add_f32 v[130:131], v[32:33], v[130:131]
	v_pk_add_f32 v[132:133], v[34:35], v[132:133]
	global_store_dwordx4 v[146:147], v[138:141], off offset:512
	global_store_dwordx4 v[146:147], v[130:133], off offset:528
	v_add_u32_e32 v182, 0x80, v176
	v_ashrrev_i32_e32 v183, 31, v182
	v_lshlrev_b64 v[130:131], 11, v[182:183]
	v_add_u32_e32 v190, 0x90, v176
	v_lshl_add_u64 v[130:131], v[136:137], 0, v[130:131]
	v_ashrrev_i32_e32 v191, 31, v190
	flat_load_dwordx4 v[138:141], v[130:131]
	flat_load_dwordx4 v[142:145], v[130:131] offset:256
	v_lshlrev_b64 v[130:131], 11, v[190:191]
	v_add_u32_e32 v192, 0xa0, v176
	v_lshl_add_u64 v[130:131], v[136:137], 0, v[130:131]
	v_ashrrev_i32_e32 v193, 31, v192
	flat_load_dwordx4 v[146:149], v[130:131]
	flat_load_dwordx4 v[150:153], v[130:131] offset:256
	v_lshlrev_b64 v[130:131], 11, v[192:193]
	v_add_u32_e32 v194, 0xb0, v176
	v_lshl_add_u64 v[130:131], v[136:137], 0, v[130:131]
	v_ashrrev_i32_e32 v195, 31, v194
	flat_load_dwordx4 v[154:157], v[130:131]
	flat_load_dwordx4 v[158:161], v[130:131] offset:256
	v_lshlrev_b64 v[130:131], 11, v[194:195]
	v_lshl_add_u64 v[130:131], v[136:137], 0, v[130:131]
	flat_load_dwordx4 v[178:181], v[130:131]
	s_nop 0
	flat_load_dwordx4 v[130:133], v[130:131] offset:256
	v_lshlrev_b64 v[136:137], 12, v[182:183]
	v_lshl_add_u64 v[196:197], v[134:135], 0, v[136:137]
	s_waitcnt vmcnt(0) lgkmcnt(0)
; __device__ __forceinline__ float lo16(unsigned v) { return __uint_as_float(v << 16); }
; __device__ __forceinline__ float hi16(unsigned v) { return __uint_as_float(v & 0xffff0000u); }
;   __device__ __forceinline__ void operator()(const f32x4 (&acc)[2][2][4][2], const pg8::Unit& u, int wr, int wc, int fr, int fq) const {
;     ...
; #pragma unroll
;         for (int m = 0; m < 4; ++m) {
;           const int row = row0 + ai * 128 + m * 16;
; #pragma unroll
;           for (int bj = 0; bj < 2; ++bj) {
;             float* d = xo + (size_t)row * DM + col0 + bj * 128;
;             const u32x4 x4 = xv[m][bj];
;             f32x4 o0 = acc[ai][bj][m][0], o1 = acc[ai][bj][m][1];
;             o0[0] += lo16(x4.x); o0[1] += hi16(x4.x); o0[2] += lo16(x4.y); o0[3] += hi16(x4.y); o1[0] += lo16(x4.z); o1[1] += hi16(x4.z); o1[2] += lo16(x4.w); o1[3] += hi16(x4.w);
;             *(f32x4*)d = o0; *(f32x4*)(d + 4) = o1;
;           }
;         }
	v_lshlrev_b32_e32 v136, 16, v138
	v_and_b32_e32 v137, 0xffff0000, v138
	v_lshlrev_b32_e32 v138, 16, v139
	v_and_b32_e32 v139, 0xffff0000, v139
	v_pk_add_f32 v[136:137], v[94:95], v[136:137]
	v_pk_add_f32 v[138:139], v[96:97], v[138:139]
	v_lshlrev_b32_e32 v182, 16, v140
	v_and_b32_e32 v183, 0xffff0000, v140
	v_lshlrev_b32_e32 v140, 16, v141
	v_and_b32_e32 v141, 0xffff0000, v141
	v_pk_add_f32 v[182:183], v[90:91], v[182:183]
	v_pk_add_f32 v[184:185], v[92:93], v[140:141]
	global_store_dwordx4 v[196:197], v[136:139], off
	global_store_dwordx4 v[196:197], v[182:185], off offset:16
	v_lshlrev_b32_e32 v140, 16, v144
	v_lshlrev_b32_e32 v136, 16, v142
	v_and_b32_e32 v137, 0xffff0000, v142
	v_lshlrev_b32_e32 v138, 16, v143
	v_and_b32_e32 v139, 0xffff0000, v143
	v_pk_add_f32 v[136:137], v[28:29], v[136:137]
	v_pk_add_f32 v[138:139], v[30:31], v[138:139]
	v_and_b32_e32 v141, 0xffff0000, v144
	v_lshlrev_b32_e32 v142, 16, v145
	v_and_b32_e32 v143, 0xffff0000, v145
	v_pk_add_f32 v[140:141], v[24:25], v[140:141]
	v_pk_add_f32 v[142:143], v[26:27], v[142:143]
	global_store_dwordx4 v[196:197], v[136:139], off offset:512
	global_store_dwordx4 v[196:197], v[140:143], off offset:528
	s_nop 0
	v_lshlrev_b64 v[136:137], 12, v[190:191]
	v_lshl_add_u64 v[144:145], v[134:135], 0, v[136:137]
	v_lshlrev_b32_e32 v136, 16, v146
	v_and_b32_e32 v137, 0xffff0000, v146
	v_lshlrev_b32_e32 v138, 16, v147
	v_and_b32_e32 v139, 0xffff0000, v147
	v_pk_add_f32 v[136:137], v[86:87], v[136:137]
	v_pk_add_f32 v[138:139], v[88:89], v[138:139]
	v_lshlrev_b32_e32 v140, 16, v148
	v_and_b32_e32 v141, 0xffff0000, v148
	v_lshlrev_b32_e32 v142, 16, v149
	v_and_b32_e32 v143, 0xffff0000, v149
	v_pk_add_f32 v[140:141], v[82:83], v[140:141]
	v_pk_add_f32 v[142:143], v[84:85], v[142:143]
	global_store_dwordx4 v[144:145], v[136:139], off
	global_store_dwordx4 v[144:145], v[140:143], off offset:16
	s_nop 0
	v_lshlrev_b32_e32 v136, 16, v150
	v_and_b32_e32 v137, 0xffff0000, v150
	v_lshlrev_b32_e32 v138, 16, v151
	v_and_b32_e32 v139, 0xffff0000, v151
	v_pk_add_f32 v[136:137], v[20:21], v[136:137]
	v_pk_add_f32 v[138:139], v[22:23], v[138:139]
	v_lshlrev_b32_e32 v140, 16, v152
	v_and_b32_e32 v141, 0xffff0000, v152
	v_lshlrev_b32_e32 v142, 16, v153
	v_and_b32_e32 v143, 0xffff0000, v153
	v_pk_add_f32 v[140:141], v[16:17], v[140:141]
	v_pk_add_f32 v[142:143], v[18:19], v[142:143]
	global_store_dwordx4 v[144:145], v[136:139], off offset:512
	global_store_dwordx4 v[144:145], v[140:143], off offset:528
	s_nop 0
	v_lshlrev_b64 v[136:137], 12, v[192:193]
	v_lshl_add_u64 v[144:145], v[134:135], 0, v[136:137]
	v_lshlrev_b32_e32 v136, 16, v154
	v_and_b32_e32 v137, 0xffff0000, v154
	v_lshlrev_b32_e32 v138, 16, v155
	v_and_b32_e32 v139, 0xffff0000, v155
	v_pk_add_f32 v[136:137], v[76:77], v[136:137]
	v_pk_add_f32 v[138:139], v[78:79], v[138:139]
	v_lshlrev_b32_e32 v140, 16, v156
	v_and_b32_e32 v141, 0xffff0000, v156
	v_lshlrev_b32_e32 v142, 16, v157
	v_and_b32_e32 v143, 0xffff0000, v157
	v_pk_add_f32 v[140:141], v[72:73], v[140:141]
	v_pk_add_f32 v[142:143], v[74:75], v[142:143]
	global_store_dwordx4 v[144:145], v[136:139], off
	global_store_dwordx4 v[144:145], v[140:143], off offset:16
	s_nop 0
	v_lshlrev_b32_e32 v136, 16, v158
	v_and_b32_e32 v137, 0xffff0000, v158
	v_lshlrev_b32_e32 v138, 16, v159
	v_and_b32_e32 v139, 0xffff0000, v159
	v_pk_add_f32 v[136:137], v[12:13], v[136:137]
	v_pk_add_f32 v[138:139], v[14:15], v[138:139]
	v_lshlrev_b32_e32 v140, 16, v160
	v_and_b32_e32 v141, 0xffff0000, v160
	v_lshlrev_b32_e32 v142, 16, v161
	v_and_b32_e32 v143, 0xffff0000, v161
	v_pk_add_f32 v[140:141], v[8:9], v[140:141]
	v_pk_add_f32 v[142:143], v[10:11], v[142:143]
	global_store_dwordx4 v[144:145], v[136:139], off offset:512
	global_store_dwordx4 v[144:145], v[140:143], off offset:528
	s_nop 0
	v_lshlrev_b64 v[136:137], 12, v[194:195]
	v_lshl_add_u64 v[142:143], v[134:135], 0, v[136:137]
	v_lshlrev_b32_e32 v134, 16, v178
	v_and_b32_e32 v135, 0xffff0000, v178
	v_lshlrev_b32_e32 v136, 16, v179
	v_and_b32_e32 v137, 0xffff0000, v179
	v_pk_add_f32 v[134:135], v[68:69], v[134:135]
	v_pk_add_f32 v[136:137], v[70:71], v[136:137]
	v_lshlrev_b32_e32 v138, 16, v180
	v_and_b32_e32 v139, 0xffff0000, v180
	v_lshlrev_b32_e32 v140, 16, v181
	v_and_b32_e32 v141, 0xffff0000, v181
	v_pk_add_f32 v[138:139], v[64:65], v[138:139]
	v_pk_add_f32 v[140:141], v[66:67], v[140:141]
	global_store_dwordx4 v[142:143], v[134:137], off
	global_store_dwordx4 v[142:143], v[138:141], off offset:16
	s_nop 0
	v_lshlrev_b32_e32 v134, 16, v130
	v_and_b32_e32 v135, 0xffff0000, v130
	v_lshlrev_b32_e32 v130, 16, v131
	v_and_b32_e32 v131, 0xffff0000, v131
	v_pk_add_f32 v[134:135], v[4:5], v[134:135]
	v_pk_add_f32 v[136:137], v[6:7], v[130:131]
	v_lshlrev_b32_e32 v130, 16, v132
	v_and_b32_e32 v131, 0xffff0000, v132
	v_lshlrev_b32_e32 v132, 16, v133
	v_and_b32_e32 v133, 0xffff0000, v133
	v_pk_add_f32 v[130:131], v[0:1], v[130:131]
	v_pk_add_f32 v[132:133], v[2:3], v[132:133]
	global_store_dwordx4 v[142:143], v[134:137], off offset:512
	global_store_dwordx4 v[142:143], v[130:133], off offset:528
	s_mov_b64 s[10:11], 0

;   __device__ __forceinline__ void operator()(const f32x4 (&acc)[2][2][4][2], const pg8::Unit& u, int wr, int wc, int fr, int fq) const {
;     ...
;     if (mode == EM_FILT) {
;       const float dmin = 3.0701134573253945f, dmax = 15.350567286626973f;
; #pragma unroll
;       for (int bj = 0; bj < 2; ++bj) {
;         const int pr = col0 + bj * 128; const int L = pr < 2048 ? 2048 : 16384; const int p0 = pr < 2048 ? pr : pr - 2048;
;         u16* G = (u16*)(ws + (L == 2048 ? O_G2K : O_G16K));
;         const float tinv = 1.0f / (float)(L - 1);
; #pragma unroll
;         for (int ai = 0; ai < 2; ++ai)
; #pragma unroll
;           for (int m = 0; m < 4; ++m) {
;             const int fc = row0 + ai * 128 + m * 16; const int order = fc >> 11, dir = (fc >> 10) & 1, c = fc & 1023;
;             const float dl = dmin + (dmax - dmin) * ((float)c * (1.0f / 1023.0f));
;             float v[8]; float dk = __expf(-(float)p0 * tinv * dl); const float dstep = __expf(-tinv * dl);
; #pragma unroll
;             for (int e = 0; e < 8; ++e) { v[e] = acc[ai][bj][m][e >> 2][e & 3] * dk; dk *= dstep; }
.LBB0_285:
	s_andn2_b64 vcc, exec, s[10:11]
	s_cbranch_vccnz .LBB0_50
	v_cmp_gt_i32_e64 s[0:1], s94, v174
	v_and_b32_e32 v143, 0x3cf, v176
	s_bitcmp1_b32 s71, 10
	s_waitcnt vmcnt(0) lgkmcnt(0)
	v_cndmask_b32_e64 v80, v226, v227, s[0:1]
	v_add_u32_e32 v130, -1, v80
	v_cvt_f32_u32_e32 v131, v130
	v_add_u32_e32 v130, 0xfffff800, v174
	v_cndmask_b32_e64 v130, v130, v174, s[0:1]
	s_mov_b64 s[12:13], -1
	v_div_scale_f32 v132, s[10:11], v131, v131, 1.0
	v_rcp_f32_e32 v133, v132
	v_div_scale_f32 v134, vcc, 1.0, v131, 1.0
	s_cselect_b64 s[10:11], -1, 0
	v_fma_f32 v135, -v132, v133, 1.0
	v_fmac_f32_e32 v133, v135, v133
	v_mul_f32_e32 v135, v134, v133
	v_fma_f32 v136, -v132, v135, v134
	v_fmac_f32_e32 v135, v136, v133
	v_cvt_f32_u32_e32 v136, v143
	v_fma_f32 v132, -v132, v135, v134
	v_cvt_f32_i32_e32 v134, v130
	v_div_fmas_f32 v132, v132, v133, v135
	v_div_fixup_f32 v141, v132, v131, 1.0
	v_cmp_eq_u32_e32 vcc, 0, v130
	v_lshlrev_b32_e32 v150, 1, v80
	v_mov_b32_e32 v149, 0
	s_and_b64 vcc, vcc, s[10:11]
	v_cndmask_b32_e32 v148, 0, v150, vcc
	v_mul_f32_e32 v131, 0x3a802008, v136
	v_mul_f32_e64 v142, v141, -v134
	v_fmamk_f32 v140, v131, 0x41447cbd, v219
	v_mul_f32_e32 v131, v140, v142
	v_mul_f32_e32 v131, 0x3fb8aa3b, v131
	v_exp_f32_e32 v132, v131
	v_mul_f32_e64 v131, v140, -v141
	v_mul_f32_e32 v131, 0x3fb8aa3b, v131
	v_exp_f32_e32 v131, v131
	s_and_b64 vcc, exec, s[10:11]
	v_mul_f32_e32 v133, v131, v132
	v_mul_f32_e32 v134, v131, v133
	v_mul_f32_e32 v135, v131, v134
	v_pk_mul_f32 v[126:127], v[132:133], v[126:127]
	v_pk_mul_f32 v[132:133], v[134:135], v[128:129]
	v_mul_f32_e32 v128, v131, v135
	v_mul_f32_e32 v129, v131, v128
	v_pk_mul_f32 v[136:137], v[128:129], v[122:123]
	v_mul_f32_e32 v122, v131, v129
	v_mul_f32_e32 v123, v131, v122
	v_pk_mul_f32 v[134:135], v[122:123], v[124:125]
	s_cbranch_vccz .LBB0_288
	v_cvt_pk_bf16_f32 v122, v126, v127
	v_cvt_pk_bf16_f32 v123, v132, v133
	v_cvt_pk_bf16_f32 v124, v136, v137
	s_mov_b64 s[12:13], 0
